# combo k=2 + phase B items-first for WGs with (bid>>4)&1
# speedup vs baseline: 1.0220x; 1.0059x over previous
; __global__ void __launch_bounds__(256, 2) hybrid_megakernel(Params p) {
;     ...
;     for (int vb = bid; vb < 512; vb += nb) {
;       { const int q2 = vb >> 3; inproj_tile<4>(p, l, (vb & 7) * 16 + (q2 & 15), 8 + (q2 >> 4), lds); }
;       if (vb < 64) cmp_item(p, l, vb, lds);
;       else {
;         const int j = vb - 64;
;         if (vb >= 256) { const int i2 = (vb - 256) >> 3; inproj_tile<2>(p, l, (vb & 7) * 16 + (i2 & 15), 24 + (i2 >> 4), lds); }
;         win_item(p, j, lds);
;         if (j + 448 < 512) win_item(p, j + 448, lds);
;         for (int it = j; it < 1536; it += 448) dil_item(p, it, lds);
;       }
;     }
.LBB0_213:
	s_or_b64 exec, exec, s[0:1]
	v_readlane_b32 s0, v235, 23
	v_readlane_b32 s1, v235, 24
	s_andn2_b64 vcc, exec, s[0:1]
	s_waitcnt lgkmcnt(0)
	v_cndmask_b32_e64 v0, 0, 1, s[0:1]
	v_cmp_ne_u32_e64 s[2:3], 1, v0
	s_barrier
	s_nop 0
	v_writelane_b32 v234, s2, 27
	s_nop 1
	v_writelane_b32 v234, s3, 28
	s_cbranch_vccnz .LBB0_298
	v_readlane_b32 s0, v234, 24
	s_mul_i32 s28, s0, 0xd00
	s_lshl_b32 s29, s0, 1
	v_readlane_b32 s30, v234, 18
	v_readlane_b32 s31, v234, 17
	v_readlane_b32 s34, v234, 14
	v_readlane_b32 s35, v234, 13
	v_readlane_b32 s36, v235, 0
	s_nop 1
	s_lshr_b32 s98, s36, 4
	s_and_b32 s98, s98, 1
	s_branch .LBB0_217
